# attention: gate loads hoisted to the start of the last key-tile pair (into idle staging registers)
# speedup vs baseline: 1.0373x; 1.0048x over previous
.Lat_m_last:
	v_add_u32_e32 v140, s64, v237
	v_add_u32_e32 v141, s65, v237
	v_add_u32_e32 v176, s69, v238
	v_add_u32_e32 v177, s70, v238
	global_load_dwordx2 v[208:209], v133, s[12:13] offset:0
	global_load_dwordx2 v[210:211], v133, s[12:13] offset:64
	global_load_dwordx2 v[212:213], v133, s[12:13] offset:16
	global_load_dwordx2 v[214:215], v133, s[12:13] offset:80
	global_load_dwordx2 v[216:217], v133, s[12:13] offset:32
	global_load_dwordx2 v[218:219], v133, s[12:13] offset:96
	global_load_dwordx2 v[220:221], v133, s[12:13] offset:48
	global_load_dwordx2 v[222:223], v133, s[12:13] offset:112
	s_waitcnt lgkmcnt(5)
	v_mfma_f32_32x32x16_bf16 v[64:79], v[160:163], v[184:187], 0
	ds_read_b128 v[152:155], v140 offset:19968
	v_exp_f32_e32 v32, v32
	v_exp_f32_e32 v33, v33
	v_add_f32_e32 v130, v130, v32
	v_add_f32_e32 v131, v131, v33
	s_waitcnt lgkmcnt(5)
	v_mfma_f32_32x32x16_bf16 v[64:79], v[164:167], v[188:191], v[64:79]
	ds_read_b128 v[156:159], v140 offset:20000
	v_cvt_pk_bf16_f32 v96, v32, v33
	v_exp_f32_e32 v34, v34
	v_exp_f32_e32 v35, v35
	v_add_f32_e32 v130, v130, v34
	s_waitcnt lgkmcnt(5)
	v_mfma_f32_32x32x16_bf16 v[64:79], v[168:171], v[192:195], v[64:79]
	ds_read_b128 v[160:163], v140 offset:20032
	v_add_f32_e32 v131, v131, v35
	v_cvt_pk_bf16_f32 v97, v34, v35
	v_exp_f32_e32 v36, v36
	v_exp_f32_e32 v37, v37
	s_waitcnt lgkmcnt(5)
	v_mfma_f32_32x32x16_bf16 v[64:79], v[172:175], v[196:199], v[64:79]
	ds_read_b128 v[164:167], v140 offset:20064
	v_add_f32_e32 v130, v130, v36
	v_add_f32_e32 v131, v131, v37
	v_cvt_pk_bf16_f32 v98, v36, v37
	v_exp_f32_e32 v38, v38
	s_waitcnt lgkmcnt(5)
	v_mfma_f32_32x32x16_bf16 v[64:79], v[144:147], v[200:203], v[64:79]
	ds_read_b128 v[168:171], v140 offset:20096
	v_exp_f32_e32 v39, v39
	v_add_f32_e32 v130, v130, v38
	v_add_f32_e32 v131, v131, v39
	v_cvt_pk_bf16_f32 v99, v38, v39
	s_waitcnt lgkmcnt(5)
	v_mfma_f32_32x32x16_bf16 v[64:79], v[148:151], v[204:207], v[64:79]
	ds_read_b128 v[172:175], v140 offset:20128
	v_exp_f32_e32 v40, v40
	v_exp_f32_e32 v41, v41
	v_add_f32_e32 v130, v130, v40
	v_add_f32_e32 v131, v131, v41
	s_waitcnt lgkmcnt(5)
	v_mfma_f32_32x32x16_bf16 v[80:95], v[152:155], v[184:187], 0
	ds_read_b64_tr_b16 v[144:145], v176 offset:8192
	ds_read_b64_tr_b16 v[146:147], v176 offset:9216
	v_cvt_pk_bf16_f32 v100, v40, v41
	v_exp_f32_e32 v42, v42
	v_exp_f32_e32 v43, v43
	v_add_f32_e32 v130, v130, v42
	s_waitcnt lgkmcnt(6)
	v_mfma_f32_32x32x16_bf16 v[80:95], v[156:159], v[188:191], v[80:95]
	ds_read_b64_tr_b16 v[148:149], v176 offset:8704
	ds_read_b64_tr_b16 v[150:151], v176 offset:9728
	v_add_f32_e32 v131, v131, v43
	v_cvt_pk_bf16_f32 v101, v42, v43
	v_exp_f32_e32 v44, v44
	v_exp_f32_e32 v45, v45
	s_waitcnt lgkmcnt(7)
	v_mfma_f32_32x32x16_bf16 v[80:95], v[160:163], v[192:195], v[80:95]
	ds_read_b64_tr_b16 v[152:153], v176 offset:10240
	ds_read_b64_tr_b16 v[154:155], v176 offset:11264
	v_add_f32_e32 v130, v130, v44
	v_add_f32_e32 v131, v131, v45
	v_cvt_pk_bf16_f32 v102, v44, v45
	v_exp_f32_e32 v46, v46
	s_waitcnt lgkmcnt(8)
	v_mfma_f32_32x32x16_bf16 v[80:95], v[164:167], v[196:199], v[80:95]
	ds_read_b64_tr_b16 v[156:157], v176 offset:10752
	ds_read_b64_tr_b16 v[158:159], v176 offset:11776
	v_exp_f32_e32 v47, v47
	v_add_f32_e32 v130, v130, v46
	v_add_f32_e32 v131, v131, v47
	v_cvt_pk_bf16_f32 v103, v46, v47
	s_waitcnt lgkmcnt(9)
	v_mfma_f32_32x32x16_bf16 v[80:95], v[168:171], v[200:203], v[80:95]
	ds_read_b64_tr_b16 v[160:161], v176 offset:12288
	ds_read_b64_tr_b16 v[162:163], v176 offset:13312
	v_exp_f32_e32 v48, v48
	v_exp_f32_e32 v49, v49
	v_add_f32_e32 v130, v130, v48
	v_add_f32_e32 v131, v131, v49
	s_waitcnt lgkmcnt(10)
	v_mfma_f32_32x32x16_bf16 v[80:95], v[172:175], v[204:207], v[80:95]
	ds_read_b64_tr_b16 v[164:165], v176 offset:12800
	ds_read_b64_tr_b16 v[166:167], v176 offset:13824
	v_cvt_pk_bf16_f32 v104, v48, v49
	v_exp_f32_e32 v50, v50
	v_exp_f32_e32 v51, v51
	v_add_f32_e32 v130, v130, v50
	s_waitcnt lgkmcnt(10)
	v_mfma_f32_32x32x16_bf16 v[0:15], v[144:147], v[112:115], v[0:15]
	ds_read_b64_tr_b16 v[168:169], v176 offset:14336
	ds_read_b64_tr_b16 v[170:171], v176 offset:15360
	v_add_f32_e32 v131, v131, v51
	v_cvt_pk_bf16_f32 v105, v50, v51
	v_exp_f32_e32 v52, v52
	v_exp_f32_e32 v53, v53
	s_waitcnt lgkmcnt(10)
	v_mfma_f32_32x32x16_bf16 v[16:31], v[148:151], v[112:115], v[16:31]
	ds_read_b64_tr_b16 v[172:173], v176 offset:14848
	ds_read_b64_tr_b16 v[174:175], v176 offset:15872
	v_add_f32_e32 v130, v130, v52
	v_add_f32_e32 v131, v131, v53
	v_cvt_pk_bf16_f32 v106, v52, v53
	v_exp_f32_e32 v54, v54
	s_waitcnt lgkmcnt(10)
	v_mfma_f32_32x32x16_bf16 v[0:15], v[152:155], v[116:119], v[0:15]
	ds_read_b64_tr_b16 v[144:145], v177 offset:0
	ds_read_b64_tr_b16 v[146:147], v177 offset:1024
	v_exp_f32_e32 v55, v55
	v_add_f32_e32 v130, v130, v54
	v_add_f32_e32 v131, v131, v55
	v_cvt_pk_bf16_f32 v107, v54, v55
	s_waitcnt lgkmcnt(10)
	v_mfma_f32_32x32x16_bf16 v[16:31], v[156:159], v[116:119], v[16:31]
	ds_read_b64_tr_b16 v[148:149], v177 offset:512
	ds_read_b64_tr_b16 v[150:151], v177 offset:1536
	v_exp_f32_e32 v56, v56
	v_exp_f32_e32 v57, v57
	v_add_f32_e32 v130, v130, v56
	v_add_f32_e32 v131, v131, v57
	s_waitcnt lgkmcnt(10)
	v_mfma_f32_32x32x16_bf16 v[0:15], v[160:163], v[120:123], v[0:15]
	ds_read_b64_tr_b16 v[152:153], v177 offset:2048
	ds_read_b64_tr_b16 v[154:155], v177 offset:3072
	v_cvt_pk_bf16_f32 v108, v56, v57
	v_exp_f32_e32 v58, v58
	v_exp_f32_e32 v59, v59
	v_add_f32_e32 v130, v130, v58
	s_waitcnt lgkmcnt(10)
	v_mfma_f32_32x32x16_bf16 v[16:31], v[164:167], v[120:123], v[16:31]
	ds_read_b64_tr_b16 v[156:157], v177 offset:2560
	ds_read_b64_tr_b16 v[158:159], v177 offset:3584
	v_add_f32_e32 v131, v131, v59
	v_cvt_pk_bf16_f32 v109, v58, v59
	v_exp_f32_e32 v60, v60
	v_exp_f32_e32 v61, v61
	s_waitcnt lgkmcnt(10)
	v_mfma_f32_32x32x16_bf16 v[0:15], v[168:171], v[124:127], v[0:15]
	ds_read_b64_tr_b16 v[160:161], v177 offset:4096
	ds_read_b64_tr_b16 v[162:163], v177 offset:5120
	v_add_f32_e32 v130, v130, v60
	v_add_f32_e32 v131, v131, v61
	v_cvt_pk_bf16_f32 v110, v60, v61
	v_exp_f32_e32 v62, v62
	s_waitcnt lgkmcnt(10)
	v_mfma_f32_32x32x16_bf16 v[16:31], v[172:175], v[124:127], v[16:31]
	ds_read_b64_tr_b16 v[164:165], v177 offset:4608
	ds_read_b64_tr_b16 v[166:167], v177 offset:5632
	v_exp_f32_e32 v63, v63
	v_add_f32_e32 v130, v130, v62
	v_add_f32_e32 v131, v131, v63
	v_cvt_pk_bf16_f32 v111, v62, v63
	s_waitcnt lgkmcnt(10)
	v_mfma_f32_32x32x16_bf16 v[0:15], v[144:147], v[96:99], v[0:15]
	ds_read_b64_tr_b16 v[168:169], v177 offset:6144
	ds_read_b64_tr_b16 v[170:171], v177 offset:7168
	v_exp_f32_e32 v64, v64
	v_exp_f32_e32 v65, v65
	v_add_f32_e32 v130, v130, v64
	v_add_f32_e32 v131, v131, v65
	v_cvt_pk_bf16_f32 v112, v64, v65
	v_exp_f32_e32 v66, v66
	v_exp_f32_e32 v67, v67
	v_add_f32_e32 v130, v130, v66
	v_add_f32_e32 v131, v131, v67
	v_cvt_pk_bf16_f32 v113, v66, v67
	s_waitcnt lgkmcnt(10)
	v_mfma_f32_32x32x16_bf16 v[16:31], v[148:151], v[96:99], v[16:31]
	ds_read_b64_tr_b16 v[172:173], v177 offset:6656
	ds_read_b64_tr_b16 v[174:175], v177 offset:7680
	v_exp_f32_e32 v68, v68
	v_exp_f32_e32 v69, v69
	v_add_f32_e32 v130, v130, v68
	v_add_f32_e32 v131, v131, v69
	v_cvt_pk_bf16_f32 v114, v68, v69
	v_exp_f32_e32 v70, v70
	v_exp_f32_e32 v71, v71
	v_add_f32_e32 v130, v130, v70
	v_add_f32_e32 v131, v131, v71
	v_cvt_pk_bf16_f32 v115, v70, v71
	s_waitcnt lgkmcnt(10)
	v_mfma_f32_32x32x16_bf16 v[0:15], v[152:155], v[100:103], v[0:15]
	v_exp_f32_e32 v72, v72
	v_exp_f32_e32 v73, v73
	v_add_f32_e32 v130, v130, v72
	v_add_f32_e32 v131, v131, v73
	v_cvt_pk_bf16_f32 v116, v72, v73
	v_exp_f32_e32 v74, v74
	v_exp_f32_e32 v75, v75
	v_add_f32_e32 v130, v130, v74
	v_add_f32_e32 v131, v131, v75
	v_cvt_pk_bf16_f32 v117, v74, v75
	s_waitcnt lgkmcnt(8)
	v_mfma_f32_32x32x16_bf16 v[16:31], v[156:159], v[100:103], v[16:31]
	v_exp_f32_e32 v76, v76
	v_exp_f32_e32 v77, v77
	v_add_f32_e32 v130, v130, v76
	v_add_f32_e32 v131, v131, v77
	v_cvt_pk_bf16_f32 v118, v76, v77
	v_exp_f32_e32 v78, v78
	v_exp_f32_e32 v79, v79
	v_add_f32_e32 v130, v130, v78
	v_add_f32_e32 v131, v131, v79
	v_cvt_pk_bf16_f32 v119, v78, v79
	s_waitcnt lgkmcnt(6)
	v_mfma_f32_32x32x16_bf16 v[0:15], v[160:163], v[104:107], v[0:15]
	v_exp_f32_e32 v80, v80
	v_exp_f32_e32 v81, v81
	v_add_f32_e32 v130, v130, v80
	v_add_f32_e32 v131, v131, v81
	v_cvt_pk_bf16_f32 v120, v80, v81
	v_exp_f32_e32 v82, v82
	v_exp_f32_e32 v83, v83
	v_add_f32_e32 v130, v130, v82
	v_add_f32_e32 v131, v131, v83
	v_cvt_pk_bf16_f32 v121, v82, v83
	s_waitcnt lgkmcnt(4)
	v_mfma_f32_32x32x16_bf16 v[16:31], v[164:167], v[104:107], v[16:31]
	v_exp_f32_e32 v84, v84
	v_exp_f32_e32 v85, v85
	v_add_f32_e32 v130, v130, v84
	v_add_f32_e32 v131, v131, v85
	v_cvt_pk_bf16_f32 v122, v84, v85
	v_exp_f32_e32 v86, v86
	v_exp_f32_e32 v87, v87
	v_add_f32_e32 v130, v130, v86
	v_add_f32_e32 v131, v131, v87
	v_cvt_pk_bf16_f32 v123, v86, v87
	s_waitcnt lgkmcnt(2)
	v_mfma_f32_32x32x16_bf16 v[0:15], v[168:171], v[108:111], v[0:15]
	v_exp_f32_e32 v88, v88
	v_exp_f32_e32 v89, v89
	v_add_f32_e32 v130, v130, v88
	v_add_f32_e32 v131, v131, v89
	v_cvt_pk_bf16_f32 v124, v88, v89
	v_exp_f32_e32 v90, v90
	v_exp_f32_e32 v91, v91
	v_add_f32_e32 v130, v130, v90
	v_add_f32_e32 v131, v131, v91
	v_cvt_pk_bf16_f32 v125, v90, v91
	s_waitcnt lgkmcnt(0)
	v_mfma_f32_32x32x16_bf16 v[16:31], v[172:175], v[108:111], v[16:31]
	v_exp_f32_e32 v92, v92
	v_exp_f32_e32 v93, v93
	v_add_f32_e32 v130, v130, v92
	v_add_f32_e32 v131, v131, v93
	v_cvt_pk_bf16_f32 v126, v92, v93
	v_exp_f32_e32 v94, v94
	v_exp_f32_e32 v95, v95
	v_add_f32_e32 v130, v130, v94
	v_add_f32_e32 v131, v131, v95
	v_cvt_pk_bf16_f32 v127, v94, v95
	v_add_u32_e32 v176, s70, v238
	ds_read_b64_tr_b16 v[144:145], v176 offset:8192
	ds_read_b64_tr_b16 v[146:147], v176 offset:9216
	ds_read_b64_tr_b16 v[148:149], v176 offset:8704
	ds_read_b64_tr_b16 v[150:151], v176 offset:9728
	ds_read_b64_tr_b16 v[152:153], v176 offset:10240
	ds_read_b64_tr_b16 v[154:155], v176 offset:11264
	ds_read_b64_tr_b16 v[156:157], v176 offset:10752
	ds_read_b64_tr_b16 v[158:159], v176 offset:11776
	ds_read_b64_tr_b16 v[160:161], v176 offset:12288
	ds_read_b64_tr_b16 v[162:163], v176 offset:13312
	ds_read_b64_tr_b16 v[164:165], v176 offset:12800
	ds_read_b64_tr_b16 v[166:167], v176 offset:13824
	s_waitcnt lgkmcnt(10)
	v_mfma_f32_32x32x16_bf16 v[0:15], v[144:147], v[112:115], v[0:15]
	ds_read_b64_tr_b16 v[168:169], v176 offset:14336
	ds_read_b64_tr_b16 v[170:171], v176 offset:15360
	s_waitcnt lgkmcnt(10)
	v_mfma_f32_32x32x16_bf16 v[16:31], v[148:151], v[112:115], v[16:31]
	ds_read_b64_tr_b16 v[172:173], v176 offset:14848
	ds_read_b64_tr_b16 v[174:175], v176 offset:15872
	s_waitcnt lgkmcnt(10)
	v_mfma_f32_32x32x16_bf16 v[0:15], v[152:155], v[116:119], v[0:15]
	s_waitcnt lgkmcnt(8)
	v_mfma_f32_32x32x16_bf16 v[16:31], v[156:159], v[116:119], v[16:31]
	s_waitcnt lgkmcnt(6)
	v_mfma_f32_32x32x16_bf16 v[0:15], v[160:163], v[120:123], v[0:15]
	s_waitcnt lgkmcnt(4)
	v_mfma_f32_32x32x16_bf16 v[16:31], v[164:167], v[120:123], v[16:31]
	s_waitcnt lgkmcnt(2)
	v_mfma_f32_32x32x16_bf16 v[0:15], v[168:171], v[124:127], v[0:15]
	s_waitcnt lgkmcnt(0)
	v_mfma_f32_32x32x16_bf16 v[16:31], v[172:175], v[124:127], v[16:31]
	v_add_f32_e32 v135, v130, v131
	v_mov_b32_e32 v128, v135
	s_nop 1
	v_permlane32_swap_b32_e32 v135, v128
	s_nop 1
	v_add_f32_e32 v135, v135, v128
	s_mov_b32 s0, 0x7149f2ca
	v_cmp_lt_f32_e32 vcc, 0xda24260, v135
	v_cmp_gt_f32_e64 s[76:77], s0, v135
	s_nop 1
	s_and_b64 s[76:77], s[76:77], vcc
	s_andn2_b64 s[76:77], exec, s[76:77]
	s_cmp_lg_u64 s[76:77], 0
	s_cselect_b32 s0, 1, 0
	v_mov_b32_e32 v128, s0
	v_lshrrev_b32_e32 v132, 6, v143
	v_lshlrev_b32_e32 v132, 2, v132
	v_add_u32_e32 v132, 131072, v132
	ds_write_b32 v132, v128
	s_waitcnt lgkmcnt(0)
	s_barrier
	v_mov_b32_e32 v132, 131072
	ds_read_b128 v[48:51], v132
	ds_read_b128 v[52:55], v132 offset:16
	v_rcp_f32_e32 v136, v135
	s_nop 0
	v_fma_f32 v128, -v135, v136, 1.0
	v_fma_f32 v136, v136, v128, v136
	s_waitcnt lgkmcnt(0)
	v_or_b32_e32 v48, v48, v49
	v_or3_b32 v48, v48, v50, v51
	v_or3_b32 v48, v48, v52, v53
	v_or3_b32 v48, v48, v54, v55
	s_nop 0
	v_readfirstlane_b32 s0, v48
	s_and_b32 s1, s9, 31
	s_lshl_b32 s1, 1, s1
	s_cmp_lg_u32 s0, 0
	s_cselect_b32 s1, s1, 0
	s_or_b32 s26, s26, s1
	s_waitcnt vmcnt(0)
	s_mov_b32 s0, 0xbfb8aa3b
	v_lshlrev_b32_e32 v56, 16, v208
	v_and_b32_e32 v57, 0xffff0000, v208
	v_lshlrev_b32_e32 v58, 16, v209
	v_and_b32_e32 v59, 0xffff0000, v209
	v_mul_f32_e32 v62, s0, v56
	v_mul_f32_e32 v63, s0, v57
	v_mul_f32_e32 v48, s0, v58
	v_mul_f32_e32 v49, s0, v59
	v_exp_f32_e32 v62, v62
	v_exp_f32_e32 v63, v63
	v_exp_f32_e32 v48, v48
	v_exp_f32_e32 v49, v49
	s_nop 0
	v_add_f32_e32 v62, 1.0, v62
	v_add_f32_e32 v63, 1.0, v63
	v_add_f32_e32 v48, 1.0, v48
	v_add_f32_e32 v49, 1.0, v49
	v_rcp_f32_e32 v62, v62
	v_rcp_f32_e32 v63, v63
	v_rcp_f32_e32 v48, v48
	v_rcp_f32_e32 v49, v49
	s_nop 0
	v_mul_f32_e32 v56, v56, v62
	v_mul_f32_e32 v57, v57, v63
	v_mul_f32_e32 v58, v58, v48
	v_mul_f32_e32 v59, v59, v49
	v_mul_f32_e32 v62, v0, v136
	v_mul_f32_e32 v63, v1, v136
	v_mul_f32_e32 v48, v2, v136
	v_mul_f32_e32 v49, v3, v136
	v_mul_f32_e32 v62, v62, v56
	v_mul_f32_e32 v63, v63, v57
	v_mul_f32_e32 v48, v48, v58
	v_mul_f32_e32 v49, v49, v59
	v_cvt_pk_bf16_f32 v60, v62, v63
	v_cvt_pk_bf16_f32 v61, v48, v49
	global_store_dwordx2 v134, v[60:61], s[14:15] offset:0
	s_nop 0
	v_lshlrev_b32_e32 v56, 16, v210
	v_and_b32_e32 v57, 0xffff0000, v210
	v_lshlrev_b32_e32 v58, 16, v211
	v_and_b32_e32 v59, 0xffff0000, v211
	v_mul_f32_e32 v62, s0, v56
	v_mul_f32_e32 v63, s0, v57
	v_mul_f32_e32 v48, s0, v58
	v_mul_f32_e32 v49, s0, v59
	v_exp_f32_e32 v62, v62
	v_exp_f32_e32 v63, v63
	v_exp_f32_e32 v48, v48
	v_exp_f32_e32 v49, v49
	s_nop 0
	v_add_f32_e32 v62, 1.0, v62
	v_add_f32_e32 v63, 1.0, v63
	v_add_f32_e32 v48, 1.0, v48
	v_add_f32_e32 v49, 1.0, v49
	v_rcp_f32_e32 v62, v62
	v_rcp_f32_e32 v63, v63
	v_rcp_f32_e32 v48, v48
	v_rcp_f32_e32 v49, v49
	s_nop 0
	v_mul_f32_e32 v56, v56, v62
	v_mul_f32_e32 v57, v57, v63
	v_mul_f32_e32 v58, v58, v48
	v_mul_f32_e32 v59, v59, v49
	v_mul_f32_e32 v62, v16, v136
	v_mul_f32_e32 v63, v17, v136
	v_mul_f32_e32 v48, v18, v136
	v_mul_f32_e32 v49, v19, v136
	v_mul_f32_e32 v62, v62, v56
	v_mul_f32_e32 v63, v63, v57
	v_mul_f32_e32 v48, v48, v58
	v_mul_f32_e32 v49, v49, v59
	v_cvt_pk_bf16_f32 v60, v62, v63
	v_cvt_pk_bf16_f32 v61, v48, v49
	global_store_dwordx2 v134, v[60:61], s[14:15] offset:64
	s_nop 0
	v_lshlrev_b32_e32 v56, 16, v212
	v_and_b32_e32 v57, 0xffff0000, v212
	v_lshlrev_b32_e32 v58, 16, v213
	v_and_b32_e32 v59, 0xffff0000, v213
	v_mul_f32_e32 v62, s0, v56
	v_mul_f32_e32 v63, s0, v57
	v_mul_f32_e32 v48, s0, v58
	v_mul_f32_e32 v49, s0, v59
	v_exp_f32_e32 v62, v62
	v_exp_f32_e32 v63, v63
	v_exp_f32_e32 v48, v48
	v_exp_f32_e32 v49, v49
	s_nop 0
	v_add_f32_e32 v62, 1.0, v62
	v_add_f32_e32 v63, 1.0, v63
	v_add_f32_e32 v48, 1.0, v48
	v_add_f32_e32 v49, 1.0, v49
	v_rcp_f32_e32 v62, v62
	v_rcp_f32_e32 v63, v63
	v_rcp_f32_e32 v48, v48
	v_rcp_f32_e32 v49, v49
	s_nop 0
	v_mul_f32_e32 v56, v56, v62
	v_mul_f32_e32 v57, v57, v63
	v_mul_f32_e32 v58, v58, v48
	v_mul_f32_e32 v59, v59, v49
	v_mul_f32_e32 v62, v4, v136
	v_mul_f32_e32 v63, v5, v136
	v_mul_f32_e32 v48, v6, v136
	v_mul_f32_e32 v49, v7, v136
	v_mul_f32_e32 v62, v62, v56
	v_mul_f32_e32 v63, v63, v57
	v_mul_f32_e32 v48, v48, v58
	v_mul_f32_e32 v49, v49, v59
	v_cvt_pk_bf16_f32 v60, v62, v63
	v_cvt_pk_bf16_f32 v61, v48, v49
	global_store_dwordx2 v134, v[60:61], s[14:15] offset:16
	s_nop 0
	v_lshlrev_b32_e32 v56, 16, v214
	v_and_b32_e32 v57, 0xffff0000, v214
	v_lshlrev_b32_e32 v58, 16, v215
	v_and_b32_e32 v59, 0xffff0000, v215
	v_mul_f32_e32 v62, s0, v56
	v_mul_f32_e32 v63, s0, v57
	v_mul_f32_e32 v48, s0, v58
	v_mul_f32_e32 v49, s0, v59
	v_exp_f32_e32 v62, v62
	v_exp_f32_e32 v63, v63
	v_exp_f32_e32 v48, v48
	v_exp_f32_e32 v49, v49
	s_nop 0
	v_add_f32_e32 v62, 1.0, v62
	v_add_f32_e32 v63, 1.0, v63
	v_add_f32_e32 v48, 1.0, v48
	v_add_f32_e32 v49, 1.0, v49
	v_rcp_f32_e32 v62, v62
	v_rcp_f32_e32 v63, v63
	v_rcp_f32_e32 v48, v48
	v_rcp_f32_e32 v49, v49
	s_nop 0
	v_mul_f32_e32 v56, v56, v62
	v_mul_f32_e32 v57, v57, v63
	v_mul_f32_e32 v58, v58, v48
	v_mul_f32_e32 v59, v59, v49
	v_mul_f32_e32 v62, v20, v136
	v_mul_f32_e32 v63, v21, v136
	v_mul_f32_e32 v48, v22, v136
	v_mul_f32_e32 v49, v23, v136
	v_mul_f32_e32 v62, v62, v56
	v_mul_f32_e32 v63, v63, v57
	v_mul_f32_e32 v48, v48, v58
	v_mul_f32_e32 v49, v49, v59
	v_cvt_pk_bf16_f32 v60, v62, v63
	v_cvt_pk_bf16_f32 v61, v48, v49
	global_store_dwordx2 v134, v[60:61], s[14:15] offset:80
	s_nop 0
	v_lshlrev_b32_e32 v56, 16, v216
	v_and_b32_e32 v57, 0xffff0000, v216
	v_lshlrev_b32_e32 v58, 16, v217
	v_and_b32_e32 v59, 0xffff0000, v217
	v_mul_f32_e32 v62, s0, v56
	v_mul_f32_e32 v63, s0, v57
	v_mul_f32_e32 v48, s0, v58
	v_mul_f32_e32 v49, s0, v59
	v_exp_f32_e32 v62, v62
	v_exp_f32_e32 v63, v63
	v_exp_f32_e32 v48, v48
	v_exp_f32_e32 v49, v49
	s_nop 0
	v_add_f32_e32 v62, 1.0, v62
	v_add_f32_e32 v63, 1.0, v63
	v_add_f32_e32 v48, 1.0, v48
	v_add_f32_e32 v49, 1.0, v49
	v_rcp_f32_e32 v62, v62
	v_rcp_f32_e32 v63, v63
	v_rcp_f32_e32 v48, v48
	v_rcp_f32_e32 v49, v49
	s_nop 0
	v_mul_f32_e32 v56, v56, v62
	v_mul_f32_e32 v57, v57, v63
	v_mul_f32_e32 v58, v58, v48
	v_mul_f32_e32 v59, v59, v49
	v_mul_f32_e32 v62, v8, v136
	v_mul_f32_e32 v63, v9, v136
	v_mul_f32_e32 v48, v10, v136
	v_mul_f32_e32 v49, v11, v136
	v_mul_f32_e32 v62, v62, v56
	v_mul_f32_e32 v63, v63, v57
	v_mul_f32_e32 v48, v48, v58
	v_mul_f32_e32 v49, v49, v59
	v_cvt_pk_bf16_f32 v60, v62, v63
	v_cvt_pk_bf16_f32 v61, v48, v49
	global_store_dwordx2 v134, v[60:61], s[14:15] offset:32
	s_nop 0
	v_lshlrev_b32_e32 v56, 16, v218
	v_and_b32_e32 v57, 0xffff0000, v218
	v_lshlrev_b32_e32 v58, 16, v219
	v_and_b32_e32 v59, 0xffff0000, v219
	v_mul_f32_e32 v62, s0, v56
	v_mul_f32_e32 v63, s0, v57
	v_mul_f32_e32 v48, s0, v58
	v_mul_f32_e32 v49, s0, v59
	v_exp_f32_e32 v62, v62
	v_exp_f32_e32 v63, v63
	v_exp_f32_e32 v48, v48
	v_exp_f32_e32 v49, v49
	s_nop 0
	v_add_f32_e32 v62, 1.0, v62
	v_add_f32_e32 v63, 1.0, v63
	v_add_f32_e32 v48, 1.0, v48
	v_add_f32_e32 v49, 1.0, v49
	v_rcp_f32_e32 v62, v62
	v_rcp_f32_e32 v63, v63
	v_rcp_f32_e32 v48, v48
	v_rcp_f32_e32 v49, v49
	s_nop 0
	v_mul_f32_e32 v56, v56, v62
	v_mul_f32_e32 v57, v57, v63
	v_mul_f32_e32 v58, v58, v48
	v_mul_f32_e32 v59, v59, v49
	v_mul_f32_e32 v62, v24, v136
	v_mul_f32_e32 v63, v25, v136
	v_mul_f32_e32 v48, v26, v136
	v_mul_f32_e32 v49, v27, v136
	v_mul_f32_e32 v62, v62, v56
	v_mul_f32_e32 v63, v63, v57
	v_mul_f32_e32 v48, v48, v58
	v_mul_f32_e32 v49, v49, v59
	v_cvt_pk_bf16_f32 v60, v62, v63
	v_cvt_pk_bf16_f32 v61, v48, v49
	global_store_dwordx2 v134, v[60:61], s[14:15] offset:96
	s_nop 0
	v_lshlrev_b32_e32 v56, 16, v220
	v_and_b32_e32 v57, 0xffff0000, v220
	v_lshlrev_b32_e32 v58, 16, v221
	v_and_b32_e32 v59, 0xffff0000, v221
	v_mul_f32_e32 v62, s0, v56
	v_mul_f32_e32 v63, s0, v57
	v_mul_f32_e32 v48, s0, v58
	v_mul_f32_e32 v49, s0, v59
	v_exp_f32_e32 v62, v62
	v_exp_f32_e32 v63, v63
	v_exp_f32_e32 v48, v48
	v_exp_f32_e32 v49, v49
	s_nop 0
	v_add_f32_e32 v62, 1.0, v62
	v_add_f32_e32 v63, 1.0, v63
	v_add_f32_e32 v48, 1.0, v48
	v_add_f32_e32 v49, 1.0, v49
	v_rcp_f32_e32 v62, v62
	v_rcp_f32_e32 v63, v63
	v_rcp_f32_e32 v48, v48
	v_rcp_f32_e32 v49, v49
	s_nop 0
	v_mul_f32_e32 v56, v56, v62
	v_mul_f32_e32 v57, v57, v63
	v_mul_f32_e32 v58, v58, v48
	v_mul_f32_e32 v59, v59, v49
	v_mul_f32_e32 v62, v12, v136
	v_mul_f32_e32 v63, v13, v136
	v_mul_f32_e32 v48, v14, v136
	v_mul_f32_e32 v49, v15, v136
	v_mul_f32_e32 v62, v62, v56
	v_mul_f32_e32 v63, v63, v57
	v_mul_f32_e32 v48, v48, v58
	v_mul_f32_e32 v49, v49, v59
	v_cvt_pk_bf16_f32 v60, v62, v63
	v_cvt_pk_bf16_f32 v61, v48, v49
	global_store_dwordx2 v134, v[60:61], s[14:15] offset:48
	s_nop 0
	v_lshlrev_b32_e32 v56, 16, v222
	v_and_b32_e32 v57, 0xffff0000, v222
	v_lshlrev_b32_e32 v58, 16, v223
	v_and_b32_e32 v59, 0xffff0000, v223
	v_mul_f32_e32 v62, s0, v56
	v_mul_f32_e32 v63, s0, v57
	v_mul_f32_e32 v48, s0, v58
	v_mul_f32_e32 v49, s0, v59
	v_exp_f32_e32 v62, v62
	v_exp_f32_e32 v63, v63
	v_exp_f32_e32 v48, v48
	v_exp_f32_e32 v49, v49
	s_nop 0
	v_add_f32_e32 v62, 1.0, v62
	v_add_f32_e32 v63, 1.0, v63
	v_add_f32_e32 v48, 1.0, v48
	v_add_f32_e32 v49, 1.0, v49
	v_rcp_f32_e32 v62, v62
	v_rcp_f32_e32 v63, v63
	v_rcp_f32_e32 v48, v48
	v_rcp_f32_e32 v49, v49
	s_nop 0
	v_mul_f32_e32 v56, v56, v62
	v_mul_f32_e32 v57, v57, v63
	v_mul_f32_e32 v58, v58, v48
	v_mul_f32_e32 v59, v59, v49
	v_mul_f32_e32 v62, v28, v136
	v_mul_f32_e32 v63, v29, v136
	v_mul_f32_e32 v48, v30, v136
	v_mul_f32_e32 v49, v31, v136
	v_mul_f32_e32 v62, v62, v56
	v_mul_f32_e32 v63, v63, v57
	v_mul_f32_e32 v48, v48, v58
	v_mul_f32_e32 v49, v49, v59
	v_cvt_pk_bf16_f32 v60, v62, v63
	v_cvt_pk_bf16_f32 v61, v48, v49
	global_store_dwordx2 v134, v[60:61], s[14:15] offset:112
	s_nop 0
	s_branch .Lat_next

.Lat_g_last:
	v_add_u32_e32 v140, s64, v237
	v_add_u32_e32 v141, s65, v237
	v_add_u32_e32 v176, s69, v238
	v_add_u32_e32 v177, s70, v238
	global_load_dwordx2 v[208:209], v133, s[12:13] offset:0
	global_load_dwordx2 v[210:211], v133, s[12:13] offset:64
	global_load_dwordx2 v[212:213], v133, s[12:13] offset:16
	global_load_dwordx2 v[214:215], v133, s[12:13] offset:80
	global_load_dwordx2 v[216:217], v133, s[12:13] offset:32
	global_load_dwordx2 v[218:219], v133, s[12:13] offset:96
	global_load_dwordx2 v[220:221], v133, s[12:13] offset:48
	global_load_dwordx2 v[222:223], v133, s[12:13] offset:112
	s_waitcnt lgkmcnt(5)
	v_mfma_f32_32x32x16_bf16 v[64:79], v[144:147], v[184:187], 0
	ds_read_b128 v[168:171], v140 offset:13888
	v_exp_f32_e32 v32, v32
	v_exp_f32_e32 v33, v33
	v_add_f32_e32 v130, v130, v32
	v_add_f32_e32 v131, v131, v33
	v_cvt_pk_bf16_f32 v96, v32, v33
	s_waitcnt lgkmcnt(5)
	v_mfma_f32_32x32x16_bf16 v[64:79], v[148:151], v[188:191], v[64:79]
	ds_read_b128 v[172:175], v140 offset:13920
	v_exp_f32_e32 v34, v34
	v_exp_f32_e32 v35, v35
	v_add_f32_e32 v130, v130, v34
	v_add_f32_e32 v131, v131, v35
	v_cvt_pk_bf16_f32 v97, v34, v35
	s_waitcnt lgkmcnt(5)
	v_mfma_f32_32x32x16_bf16 v[64:79], v[152:155], v[192:195], v[64:79]
	ds_read_b64_tr_b16 v[144:145], v176 offset:8192
	ds_read_b64_tr_b16 v[146:147], v176 offset:9216
	v_exp_f32_e32 v36, v36
	v_exp_f32_e32 v37, v37
	v_add_f32_e32 v130, v130, v36
	v_add_f32_e32 v131, v131, v37
	v_cvt_pk_bf16_f32 v98, v36, v37
	s_waitcnt lgkmcnt(6)
	v_mfma_f32_32x32x16_bf16 v[64:79], v[156:159], v[196:199], v[64:79]
	ds_read_b64_tr_b16 v[148:149], v176 offset:8704
	ds_read_b64_tr_b16 v[150:151], v176 offset:9728
	v_exp_f32_e32 v38, v38
	v_exp_f32_e32 v39, v39
	v_add_f32_e32 v130, v130, v38
	v_add_f32_e32 v131, v131, v39
	v_cvt_pk_bf16_f32 v99, v38, v39
	s_waitcnt lgkmcnt(7)
	v_mfma_f32_32x32x16_bf16 v[80:95], v[160:163], v[184:187], 0
	ds_read_b64_tr_b16 v[152:153], v176 offset:10240
	ds_read_b64_tr_b16 v[154:155], v176 offset:11264
	v_exp_f32_e32 v40, v40
	v_exp_f32_e32 v41, v41
	v_add_f32_e32 v130, v130, v40
	v_add_f32_e32 v131, v131, v41
	v_cvt_pk_bf16_f32 v100, v40, v41
	s_waitcnt lgkmcnt(8)
	v_mfma_f32_32x32x16_bf16 v[80:95], v[164:167], v[188:191], v[80:95]
	ds_read_b64_tr_b16 v[156:157], v176 offset:10752
	ds_read_b64_tr_b16 v[158:159], v176 offset:11776
	v_exp_f32_e32 v42, v42
	v_exp_f32_e32 v43, v43
	v_add_f32_e32 v130, v130, v42
	v_add_f32_e32 v131, v131, v43
	v_cvt_pk_bf16_f32 v101, v42, v43
	s_waitcnt lgkmcnt(9)
	v_mfma_f32_32x32x16_bf16 v[80:95], v[168:171], v[192:195], v[80:95]
	ds_read_b64_tr_b16 v[160:161], v176 offset:12288
	ds_read_b64_tr_b16 v[162:163], v176 offset:13312
	v_exp_f32_e32 v44, v44
	v_exp_f32_e32 v45, v45
	v_add_f32_e32 v130, v130, v44
	v_add_f32_e32 v131, v131, v45
	v_cvt_pk_bf16_f32 v102, v44, v45
	s_waitcnt lgkmcnt(10)
	v_mfma_f32_32x32x16_bf16 v[80:95], v[172:175], v[196:199], v[80:95]
	ds_read_b64_tr_b16 v[164:165], v176 offset:12800
	ds_read_b64_tr_b16 v[166:167], v176 offset:13824
	v_exp_f32_e32 v46, v46
	v_exp_f32_e32 v47, v47
	v_add_f32_e32 v130, v130, v46
	v_add_f32_e32 v131, v131, v47
	v_cvt_pk_bf16_f32 v103, v46, v47
	s_waitcnt lgkmcnt(10)
	v_mfma_f32_32x32x16_bf16 v[0:15], v[144:147], v[112:115], v[0:15]
	ds_read_b64_tr_b16 v[168:169], v176 offset:14336
	ds_read_b64_tr_b16 v[170:171], v176 offset:15360
	v_exp_f32_e32 v48, v48
	v_exp_f32_e32 v49, v49
	v_add_f32_e32 v130, v130, v48
	v_add_f32_e32 v131, v131, v49
	v_cvt_pk_bf16_f32 v104, v48, v49
	s_waitcnt lgkmcnt(10)
	v_mfma_f32_32x32x16_bf16 v[16:31], v[148:151], v[112:115], v[16:31]
	ds_read_b64_tr_b16 v[172:173], v176 offset:14848
	ds_read_b64_tr_b16 v[174:175], v176 offset:15872
	v_exp_f32_e32 v50, v50
	v_exp_f32_e32 v51, v51
	v_add_f32_e32 v130, v130, v50
	v_add_f32_e32 v131, v131, v51
	v_cvt_pk_bf16_f32 v105, v50, v51
	s_waitcnt lgkmcnt(10)
	v_mfma_f32_32x32x16_bf16 v[0:15], v[152:155], v[116:119], v[0:15]
	ds_read_b64_tr_b16 v[144:145], v177 offset:0
	ds_read_b64_tr_b16 v[146:147], v177 offset:1024
	v_exp_f32_e32 v52, v52
	v_exp_f32_e32 v53, v53
	v_add_f32_e32 v130, v130, v52
	v_add_f32_e32 v131, v131, v53
	v_cvt_pk_bf16_f32 v106, v52, v53
	s_waitcnt lgkmcnt(10)
	v_mfma_f32_32x32x16_bf16 v[16:31], v[156:159], v[116:119], v[16:31]
	ds_read_b64_tr_b16 v[148:149], v177 offset:512
	ds_read_b64_tr_b16 v[150:151], v177 offset:1536
	v_exp_f32_e32 v54, v54
	v_exp_f32_e32 v55, v55
	v_add_f32_e32 v130, v130, v54
	v_add_f32_e32 v131, v131, v55
	v_cvt_pk_bf16_f32 v107, v54, v55
	s_waitcnt lgkmcnt(10)
	v_mfma_f32_32x32x16_bf16 v[0:15], v[160:163], v[120:123], v[0:15]
	ds_read_b64_tr_b16 v[152:153], v177 offset:2048
	ds_read_b64_tr_b16 v[154:155], v177 offset:3072
	v_exp_f32_e32 v56, v56
	v_exp_f32_e32 v57, v57
	v_add_f32_e32 v130, v130, v56
	v_add_f32_e32 v131, v131, v57
	v_cvt_pk_bf16_f32 v108, v56, v57
	s_waitcnt lgkmcnt(10)
	v_mfma_f32_32x32x16_bf16 v[16:31], v[164:167], v[120:123], v[16:31]
	ds_read_b64_tr_b16 v[156:157], v177 offset:2560
	ds_read_b64_tr_b16 v[158:159], v177 offset:3584
	v_exp_f32_e32 v58, v58
	v_exp_f32_e32 v59, v59
	v_add_f32_e32 v130, v130, v58
	v_add_f32_e32 v131, v131, v59
	v_cvt_pk_bf16_f32 v109, v58, v59
	s_waitcnt lgkmcnt(10)
	v_mfma_f32_32x32x16_bf16 v[0:15], v[168:171], v[124:127], v[0:15]
	ds_read_b64_tr_b16 v[160:161], v177 offset:4096
	ds_read_b64_tr_b16 v[162:163], v177 offset:5120
	v_exp_f32_e32 v60, v60
	v_exp_f32_e32 v61, v61
	v_add_f32_e32 v130, v130, v60
	v_add_f32_e32 v131, v131, v61
	v_cvt_pk_bf16_f32 v110, v60, v61
	s_waitcnt lgkmcnt(10)
	v_mfma_f32_32x32x16_bf16 v[16:31], v[172:175], v[124:127], v[16:31]
	ds_read_b64_tr_b16 v[164:165], v177 offset:4608
	ds_read_b64_tr_b16 v[166:167], v177 offset:5632
	v_exp_f32_e32 v62, v62
	v_exp_f32_e32 v63, v63
	v_add_f32_e32 v130, v130, v62
	v_add_f32_e32 v131, v131, v63
	v_cvt_pk_bf16_f32 v111, v62, v63
	s_waitcnt lgkmcnt(10)
	v_mfma_f32_32x32x16_bf16 v[0:15], v[144:147], v[96:99], v[0:15]
	ds_read_b64_tr_b16 v[168:169], v177 offset:6144
	ds_read_b64_tr_b16 v[170:171], v177 offset:7168
	v_exp_f32_e32 v64, v64
	v_exp_f32_e32 v65, v65
	v_add_f32_e32 v130, v130, v64
	v_add_f32_e32 v131, v131, v65
	v_cvt_pk_bf16_f32 v112, v64, v65
	v_exp_f32_e32 v66, v66
	v_exp_f32_e32 v67, v67
	v_add_f32_e32 v130, v130, v66
	v_add_f32_e32 v131, v131, v67
	v_cvt_pk_bf16_f32 v113, v66, v67
	s_waitcnt lgkmcnt(10)
	v_mfma_f32_32x32x16_bf16 v[16:31], v[148:151], v[96:99], v[16:31]
	ds_read_b64_tr_b16 v[172:173], v177 offset:6656
	ds_read_b64_tr_b16 v[174:175], v177 offset:7680
	v_exp_f32_e32 v68, v68
	v_exp_f32_e32 v69, v69
	v_add_f32_e32 v130, v130, v68
	v_add_f32_e32 v131, v131, v69
	v_cvt_pk_bf16_f32 v114, v68, v69
	v_exp_f32_e32 v70, v70
	v_exp_f32_e32 v71, v71
	v_add_f32_e32 v130, v130, v70
	v_add_f32_e32 v131, v131, v71
	v_cvt_pk_bf16_f32 v115, v70, v71
	s_waitcnt lgkmcnt(10)
	v_mfma_f32_32x32x16_bf16 v[0:15], v[152:155], v[100:103], v[0:15]
	v_exp_f32_e32 v72, v72
	v_exp_f32_e32 v73, v73
	v_add_f32_e32 v130, v130, v72
	v_add_f32_e32 v131, v131, v73
	v_cvt_pk_bf16_f32 v116, v72, v73
	v_exp_f32_e32 v74, v74
	v_exp_f32_e32 v75, v75
	v_add_f32_e32 v130, v130, v74
	v_add_f32_e32 v131, v131, v75
	v_cvt_pk_bf16_f32 v117, v74, v75
	s_waitcnt lgkmcnt(8)
	v_mfma_f32_32x32x16_bf16 v[16:31], v[156:159], v[100:103], v[16:31]
	v_exp_f32_e32 v76, v76
	v_exp_f32_e32 v77, v77
	v_add_f32_e32 v130, v130, v76
	v_add_f32_e32 v131, v131, v77
	v_cvt_pk_bf16_f32 v118, v76, v77
	v_exp_f32_e32 v78, v78
	v_exp_f32_e32 v79, v79
	v_add_f32_e32 v130, v130, v78
	v_add_f32_e32 v131, v131, v79
	v_cvt_pk_bf16_f32 v119, v78, v79
	s_waitcnt lgkmcnt(6)
	v_mfma_f32_32x32x16_bf16 v[0:15], v[160:163], v[104:107], v[0:15]
	v_exp_f32_e32 v80, v80
	v_exp_f32_e32 v81, v81
	v_add_f32_e32 v130, v130, v80
	v_add_f32_e32 v131, v131, v81
	v_cvt_pk_bf16_f32 v120, v80, v81
	v_exp_f32_e32 v82, v82
	v_exp_f32_e32 v83, v83
	v_add_f32_e32 v130, v130, v82
	v_add_f32_e32 v131, v131, v83
	v_cvt_pk_bf16_f32 v121, v82, v83
	s_waitcnt lgkmcnt(4)
	v_mfma_f32_32x32x16_bf16 v[16:31], v[164:167], v[104:107], v[16:31]
	v_exp_f32_e32 v84, v84
	v_exp_f32_e32 v85, v85
	v_add_f32_e32 v130, v130, v84
	v_add_f32_e32 v131, v131, v85
	v_cvt_pk_bf16_f32 v122, v84, v85
	v_exp_f32_e32 v86, v86
	v_exp_f32_e32 v87, v87
	v_add_f32_e32 v130, v130, v86
	v_add_f32_e32 v131, v131, v87
	v_cvt_pk_bf16_f32 v123, v86, v87
	s_waitcnt lgkmcnt(2)
	v_mfma_f32_32x32x16_bf16 v[0:15], v[168:171], v[108:111], v[0:15]
	v_exp_f32_e32 v88, v88
	v_exp_f32_e32 v89, v89
	v_add_f32_e32 v130, v130, v88
	v_add_f32_e32 v131, v131, v89
	v_cvt_pk_bf16_f32 v124, v88, v89
	v_exp_f32_e32 v90, v90
	v_exp_f32_e32 v91, v91
	v_add_f32_e32 v130, v130, v90
	v_add_f32_e32 v131, v131, v91
	v_cvt_pk_bf16_f32 v125, v90, v91
	s_waitcnt lgkmcnt(0)
	v_mfma_f32_32x32x16_bf16 v[16:31], v[172:175], v[108:111], v[16:31]
	v_exp_f32_e32 v92, v92
	v_exp_f32_e32 v93, v93
	v_add_f32_e32 v130, v130, v92
	v_add_f32_e32 v131, v131, v93
	v_cvt_pk_bf16_f32 v126, v92, v93
	v_exp_f32_e32 v94, v94
	v_exp_f32_e32 v95, v95
	v_add_f32_e32 v130, v130, v94
	v_add_f32_e32 v131, v131, v95
	v_cvt_pk_bf16_f32 v127, v94, v95
	v_add_u32_e32 v176, s70, v238
	ds_read_b64_tr_b16 v[144:145], v176 offset:8192
	ds_read_b64_tr_b16 v[146:147], v176 offset:9216
	ds_read_b64_tr_b16 v[148:149], v176 offset:8704
	ds_read_b64_tr_b16 v[150:151], v176 offset:9728
	ds_read_b64_tr_b16 v[152:153], v176 offset:10240
	ds_read_b64_tr_b16 v[154:155], v176 offset:11264
	ds_read_b64_tr_b16 v[156:157], v176 offset:10752
	ds_read_b64_tr_b16 v[158:159], v176 offset:11776
	ds_read_b64_tr_b16 v[160:161], v176 offset:12288
	ds_read_b64_tr_b16 v[162:163], v176 offset:13312
	ds_read_b64_tr_b16 v[164:165], v176 offset:12800
	ds_read_b64_tr_b16 v[166:167], v176 offset:13824
	s_waitcnt lgkmcnt(10)
	v_mfma_f32_32x32x16_bf16 v[0:15], v[144:147], v[112:115], v[0:15]
	ds_read_b64_tr_b16 v[168:169], v176 offset:14336
	ds_read_b64_tr_b16 v[170:171], v176 offset:15360
	s_waitcnt lgkmcnt(10)
	v_mfma_f32_32x32x16_bf16 v[16:31], v[148:151], v[112:115], v[16:31]
	ds_read_b64_tr_b16 v[172:173], v176 offset:14848
	ds_read_b64_tr_b16 v[174:175], v176 offset:15872
	s_waitcnt lgkmcnt(10)
	v_mfma_f32_32x32x16_bf16 v[0:15], v[152:155], v[116:119], v[0:15]
	s_waitcnt lgkmcnt(8)
	v_mfma_f32_32x32x16_bf16 v[16:31], v[156:159], v[116:119], v[16:31]
	s_waitcnt lgkmcnt(6)
	v_mfma_f32_32x32x16_bf16 v[0:15], v[160:163], v[120:123], v[0:15]
	s_waitcnt lgkmcnt(4)
	v_mfma_f32_32x32x16_bf16 v[16:31], v[164:167], v[120:123], v[16:31]
	s_waitcnt lgkmcnt(2)
	v_mfma_f32_32x32x16_bf16 v[0:15], v[168:171], v[124:127], v[0:15]
	s_waitcnt lgkmcnt(0)
	v_mfma_f32_32x32x16_bf16 v[16:31], v[172:175], v[124:127], v[16:31]
	v_add_f32_e32 v135, v130, v131
	v_mov_b32_e32 v128, v135
	s_nop 1
	v_permlane32_swap_b32_e32 v135, v128
	s_nop 1
	v_add_f32_e32 v135, v135, v128
	s_mov_b32 s0, 0x7149f2ca
	v_cmp_lt_f32_e32 vcc, 0xda24260, v135
	v_cmp_gt_f32_e64 s[76:77], s0, v135
	s_nop 1
	s_and_b64 s[76:77], s[76:77], vcc
	s_andn2_b64 s[76:77], exec, s[76:77]
	s_cmp_lg_u64 s[76:77], 0
	s_cselect_b32 s0, 1, 0
	v_mov_b32_e32 v128, s0
	v_lshrrev_b32_e32 v132, 6, v143
	v_lshlrev_b32_e32 v132, 2, v132
	v_add_u32_e32 v132, 131072, v132
	ds_write_b32 v132, v128
	s_waitcnt lgkmcnt(0)
	s_barrier
	v_mov_b32_e32 v132, 131072
	ds_read_b128 v[48:51], v132
	ds_read_b128 v[52:55], v132 offset:16
	v_rcp_f32_e32 v136, v135
	s_nop 0
	v_fma_f32 v128, -v135, v136, 1.0
	v_fma_f32 v136, v136, v128, v136
	s_waitcnt lgkmcnt(0)
	v_or_b32_e32 v48, v48, v49
	v_or3_b32 v48, v48, v50, v51
	v_or3_b32 v48, v48, v52, v53
	v_or3_b32 v48, v48, v54, v55
	s_nop 0
	v_readfirstlane_b32 s0, v48
	s_and_b32 s1, s9, 31
	s_lshl_b32 s1, 1, s1
	s_cmp_lg_u32 s0, 0
	s_cselect_b32 s1, s1, 0
	s_or_b32 s26, s26, s1
	s_waitcnt vmcnt(0)
	s_mov_b32 s0, 0xbfb8aa3b
	v_lshlrev_b32_e32 v56, 16, v208
	v_and_b32_e32 v57, 0xffff0000, v208
	v_lshlrev_b32_e32 v58, 16, v209
	v_and_b32_e32 v59, 0xffff0000, v209
	v_mul_f32_e32 v62, s0, v56
	v_mul_f32_e32 v63, s0, v57
	v_mul_f32_e32 v48, s0, v58
	v_mul_f32_e32 v49, s0, v59
	v_exp_f32_e32 v62, v62
	v_exp_f32_e32 v63, v63
	v_exp_f32_e32 v48, v48
	v_exp_f32_e32 v49, v49
	s_nop 0
	v_add_f32_e32 v62, 1.0, v62
	v_add_f32_e32 v63, 1.0, v63
	v_add_f32_e32 v48, 1.0, v48
	v_add_f32_e32 v49, 1.0, v49
	v_rcp_f32_e32 v62, v62
	v_rcp_f32_e32 v63, v63
	v_rcp_f32_e32 v48, v48
	v_rcp_f32_e32 v49, v49
	s_nop 0
	v_mul_f32_e32 v56, v56, v62
	v_mul_f32_e32 v57, v57, v63
	v_mul_f32_e32 v58, v58, v48
	v_mul_f32_e32 v59, v59, v49
	v_mul_f32_e32 v62, v0, v136
	v_mul_f32_e32 v63, v1, v136
	v_mul_f32_e32 v48, v2, v136
	v_mul_f32_e32 v49, v3, v136
	v_mul_f32_e32 v62, v62, v56
	v_mul_f32_e32 v63, v63, v57
	v_mul_f32_e32 v48, v48, v58
	v_mul_f32_e32 v49, v49, v59
	v_cvt_pk_bf16_f32 v60, v62, v63
	v_cvt_pk_bf16_f32 v61, v48, v49
	global_store_dwordx2 v134, v[60:61], s[14:15] offset:0
	s_nop 0
	v_lshlrev_b32_e32 v56, 16, v210
	v_and_b32_e32 v57, 0xffff0000, v210
	v_lshlrev_b32_e32 v58, 16, v211
	v_and_b32_e32 v59, 0xffff0000, v211
	v_mul_f32_e32 v62, s0, v56
	v_mul_f32_e32 v63, s0, v57
	v_mul_f32_e32 v48, s0, v58
	v_mul_f32_e32 v49, s0, v59
	v_exp_f32_e32 v62, v62
	v_exp_f32_e32 v63, v63
	v_exp_f32_e32 v48, v48
	v_exp_f32_e32 v49, v49
	s_nop 0
	v_add_f32_e32 v62, 1.0, v62
	v_add_f32_e32 v63, 1.0, v63
	v_add_f32_e32 v48, 1.0, v48
	v_add_f32_e32 v49, 1.0, v49
	v_rcp_f32_e32 v62, v62
	v_rcp_f32_e32 v63, v63
	v_rcp_f32_e32 v48, v48
	v_rcp_f32_e32 v49, v49
	s_nop 0
	v_mul_f32_e32 v56, v56, v62
	v_mul_f32_e32 v57, v57, v63
	v_mul_f32_e32 v58, v58, v48
	v_mul_f32_e32 v59, v59, v49
	v_mul_f32_e32 v62, v16, v136
	v_mul_f32_e32 v63, v17, v136
	v_mul_f32_e32 v48, v18, v136
	v_mul_f32_e32 v49, v19, v136
	v_mul_f32_e32 v62, v62, v56
	v_mul_f32_e32 v63, v63, v57
	v_mul_f32_e32 v48, v48, v58
	v_mul_f32_e32 v49, v49, v59
	v_cvt_pk_bf16_f32 v60, v62, v63
	v_cvt_pk_bf16_f32 v61, v48, v49
	global_store_dwordx2 v134, v[60:61], s[14:15] offset:64
	s_nop 0
	v_lshlrev_b32_e32 v56, 16, v212
	v_and_b32_e32 v57, 0xffff0000, v212
	v_lshlrev_b32_e32 v58, 16, v213
	v_and_b32_e32 v59, 0xffff0000, v213
	v_mul_f32_e32 v62, s0, v56
	v_mul_f32_e32 v63, s0, v57
	v_mul_f32_e32 v48, s0, v58
	v_mul_f32_e32 v49, s0, v59
	v_exp_f32_e32 v62, v62
	v_exp_f32_e32 v63, v63
	v_exp_f32_e32 v48, v48
	v_exp_f32_e32 v49, v49
	s_nop 0
	v_add_f32_e32 v62, 1.0, v62
	v_add_f32_e32 v63, 1.0, v63
	v_add_f32_e32 v48, 1.0, v48
	v_add_f32_e32 v49, 1.0, v49
	v_rcp_f32_e32 v62, v62
	v_rcp_f32_e32 v63, v63
	v_rcp_f32_e32 v48, v48
	v_rcp_f32_e32 v49, v49
	s_nop 0
	v_mul_f32_e32 v56, v56, v62
	v_mul_f32_e32 v57, v57, v63
	v_mul_f32_e32 v58, v58, v48
	v_mul_f32_e32 v59, v59, v49
	v_mul_f32_e32 v62, v4, v136
	v_mul_f32_e32 v63, v5, v136
	v_mul_f32_e32 v48, v6, v136
	v_mul_f32_e32 v49, v7, v136
	v_mul_f32_e32 v62, v62, v56
	v_mul_f32_e32 v63, v63, v57
	v_mul_f32_e32 v48, v48, v58
	v_mul_f32_e32 v49, v49, v59
	v_cvt_pk_bf16_f32 v60, v62, v63
	v_cvt_pk_bf16_f32 v61, v48, v49
	global_store_dwordx2 v134, v[60:61], s[14:15] offset:16
	s_nop 0
	v_lshlrev_b32_e32 v56, 16, v214
	v_and_b32_e32 v57, 0xffff0000, v214
	v_lshlrev_b32_e32 v58, 16, v215
	v_and_b32_e32 v59, 0xffff0000, v215
	v_mul_f32_e32 v62, s0, v56
	v_mul_f32_e32 v63, s0, v57
	v_mul_f32_e32 v48, s0, v58
	v_mul_f32_e32 v49, s0, v59
	v_exp_f32_e32 v62, v62
	v_exp_f32_e32 v63, v63
	v_exp_f32_e32 v48, v48
	v_exp_f32_e32 v49, v49
	s_nop 0
	v_add_f32_e32 v62, 1.0, v62
	v_add_f32_e32 v63, 1.0, v63
	v_add_f32_e32 v48, 1.0, v48
	v_add_f32_e32 v49, 1.0, v49
	v_rcp_f32_e32 v62, v62
	v_rcp_f32_e32 v63, v63
	v_rcp_f32_e32 v48, v48
	v_rcp_f32_e32 v49, v49
	s_nop 0
	v_mul_f32_e32 v56, v56, v62
	v_mul_f32_e32 v57, v57, v63
	v_mul_f32_e32 v58, v58, v48
	v_mul_f32_e32 v59, v59, v49
	v_mul_f32_e32 v62, v20, v136
	v_mul_f32_e32 v63, v21, v136
	v_mul_f32_e32 v48, v22, v136
	v_mul_f32_e32 v49, v23, v136
	v_mul_f32_e32 v62, v62, v56
	v_mul_f32_e32 v63, v63, v57
	v_mul_f32_e32 v48, v48, v58
	v_mul_f32_e32 v49, v49, v59
	v_cvt_pk_bf16_f32 v60, v62, v63
	v_cvt_pk_bf16_f32 v61, v48, v49
	global_store_dwordx2 v134, v[60:61], s[14:15] offset:80
	s_nop 0
	v_lshlrev_b32_e32 v56, 16, v216
	v_and_b32_e32 v57, 0xffff0000, v216
	v_lshlrev_b32_e32 v58, 16, v217
	v_and_b32_e32 v59, 0xffff0000, v217
	v_mul_f32_e32 v62, s0, v56
	v_mul_f32_e32 v63, s0, v57
	v_mul_f32_e32 v48, s0, v58
	v_mul_f32_e32 v49, s0, v59
	v_exp_f32_e32 v62, v62
	v_exp_f32_e32 v63, v63
	v_exp_f32_e32 v48, v48
	v_exp_f32_e32 v49, v49
	s_nop 0
	v_add_f32_e32 v62, 1.0, v62
	v_add_f32_e32 v63, 1.0, v63
	v_add_f32_e32 v48, 1.0, v48
	v_add_f32_e32 v49, 1.0, v49
	v_rcp_f32_e32 v62, v62
	v_rcp_f32_e32 v63, v63
	v_rcp_f32_e32 v48, v48
	v_rcp_f32_e32 v49, v49
	s_nop 0
	v_mul_f32_e32 v56, v56, v62
	v_mul_f32_e32 v57, v57, v63
	v_mul_f32_e32 v58, v58, v48
	v_mul_f32_e32 v59, v59, v49
	v_mul_f32_e32 v62, v8, v136
	v_mul_f32_e32 v63, v9, v136
	v_mul_f32_e32 v48, v10, v136
	v_mul_f32_e32 v49, v11, v136
	v_mul_f32_e32 v62, v62, v56
	v_mul_f32_e32 v63, v63, v57
	v_mul_f32_e32 v48, v48, v58
	v_mul_f32_e32 v49, v49, v59
	v_cvt_pk_bf16_f32 v60, v62, v63
	v_cvt_pk_bf16_f32 v61, v48, v49
	global_store_dwordx2 v134, v[60:61], s[14:15] offset:32
	s_nop 0
	v_lshlrev_b32_e32 v56, 16, v218
	v_and_b32_e32 v57, 0xffff0000, v218
	v_lshlrev_b32_e32 v58, 16, v219
	v_and_b32_e32 v59, 0xffff0000, v219
	v_mul_f32_e32 v62, s0, v56
	v_mul_f32_e32 v63, s0, v57
	v_mul_f32_e32 v48, s0, v58
	v_mul_f32_e32 v49, s0, v59
	v_exp_f32_e32 v62, v62
	v_exp_f32_e32 v63, v63
	v_exp_f32_e32 v48, v48
	v_exp_f32_e32 v49, v49
	s_nop 0
	v_add_f32_e32 v62, 1.0, v62
	v_add_f32_e32 v63, 1.0, v63
	v_add_f32_e32 v48, 1.0, v48
	v_add_f32_e32 v49, 1.0, v49
	v_rcp_f32_e32 v62, v62
	v_rcp_f32_e32 v63, v63
	v_rcp_f32_e32 v48, v48
	v_rcp_f32_e32 v49, v49
	s_nop 0
	v_mul_f32_e32 v56, v56, v62
	v_mul_f32_e32 v57, v57, v63
	v_mul_f32_e32 v58, v58, v48
	v_mul_f32_e32 v59, v59, v49
	v_mul_f32_e32 v62, v24, v136
	v_mul_f32_e32 v63, v25, v136
	v_mul_f32_e32 v48, v26, v136
	v_mul_f32_e32 v49, v27, v136
	v_mul_f32_e32 v62, v62, v56
	v_mul_f32_e32 v63, v63, v57
	v_mul_f32_e32 v48, v48, v58
	v_mul_f32_e32 v49, v49, v59
	v_cvt_pk_bf16_f32 v60, v62, v63
	v_cvt_pk_bf16_f32 v61, v48, v49
	global_store_dwordx2 v134, v[60:61], s[14:15] offset:96
	s_nop 0
	v_lshlrev_b32_e32 v56, 16, v220
	v_and_b32_e32 v57, 0xffff0000, v220
	v_lshlrev_b32_e32 v58, 16, v221
	v_and_b32_e32 v59, 0xffff0000, v221
	v_mul_f32_e32 v62, s0, v56
	v_mul_f32_e32 v63, s0, v57
	v_mul_f32_e32 v48, s0, v58
	v_mul_f32_e32 v49, s0, v59
	v_exp_f32_e32 v62, v62
	v_exp_f32_e32 v63, v63
	v_exp_f32_e32 v48, v48
	v_exp_f32_e32 v49, v49
	s_nop 0
	v_add_f32_e32 v62, 1.0, v62
	v_add_f32_e32 v63, 1.0, v63
	v_add_f32_e32 v48, 1.0, v48
	v_add_f32_e32 v49, 1.0, v49
	v_rcp_f32_e32 v62, v62
	v_rcp_f32_e32 v63, v63
	v_rcp_f32_e32 v48, v48
	v_rcp_f32_e32 v49, v49
	s_nop 0
	v_mul_f32_e32 v56, v56, v62
	v_mul_f32_e32 v57, v57, v63
	v_mul_f32_e32 v58, v58, v48
	v_mul_f32_e32 v59, v59, v49
	v_mul_f32_e32 v62, v12, v136
	v_mul_f32_e32 v63, v13, v136
	v_mul_f32_e32 v48, v14, v136
	v_mul_f32_e32 v49, v15, v136
	v_mul_f32_e32 v62, v62, v56
	v_mul_f32_e32 v63, v63, v57
	v_mul_f32_e32 v48, v48, v58
	v_mul_f32_e32 v49, v49, v59
	v_cvt_pk_bf16_f32 v60, v62, v63
	v_cvt_pk_bf16_f32 v61, v48, v49
	global_store_dwordx2 v134, v[60:61], s[14:15] offset:48
	s_nop 0
	v_lshlrev_b32_e32 v56, 16, v222
	v_and_b32_e32 v57, 0xffff0000, v222
	v_lshlrev_b32_e32 v58, 16, v223
	v_and_b32_e32 v59, 0xffff0000, v223
	v_mul_f32_e32 v62, s0, v56
	v_mul_f32_e32 v63, s0, v57
	v_mul_f32_e32 v48, s0, v58
	v_mul_f32_e32 v49, s0, v59
	v_exp_f32_e32 v62, v62
	v_exp_f32_e32 v63, v63
	v_exp_f32_e32 v48, v48
	v_exp_f32_e32 v49, v49
	s_nop 0
	v_add_f32_e32 v62, 1.0, v62
	v_add_f32_e32 v63, 1.0, v63
	v_add_f32_e32 v48, 1.0, v48
	v_add_f32_e32 v49, 1.0, v49
	v_rcp_f32_e32 v62, v62
	v_rcp_f32_e32 v63, v63
	v_rcp_f32_e32 v48, v48
	v_rcp_f32_e32 v49, v49
	s_nop 0
	v_mul_f32_e32 v56, v56, v62
	v_mul_f32_e32 v57, v57, v63
	v_mul_f32_e32 v58, v58, v48
	v_mul_f32_e32 v59, v59, v49
	v_mul_f32_e32 v62, v28, v136
	v_mul_f32_e32 v63, v29, v136
	v_mul_f32_e32 v48, v30, v136
	v_mul_f32_e32 v49, v31, v136
	v_mul_f32_e32 v62, v62, v56
	v_mul_f32_e32 v63, v63, v57
	v_mul_f32_e32 v48, v48, v58
	v_mul_f32_e32 v49, v49, v59
	v_cvt_pk_bf16_f32 v60, v62, v63
	v_cvt_pk_bf16_f32 v61, v48, v49
	global_store_dwordx2 v134, v[60:61], s[14:15] offset:112
	s_nop 0
	s_branch .Lat_next
